# v5 + static s_setprio 1 for waves 0-3 (the other half) during the attention phase
# baseline (speedup 1.0000x reference)
; __device__ __forceinline__ void phase5(const Params& p, Frame& F, char* lds) {
;     unsigned char* ws = p.ws;
;     {
;         att::Seam<CfgMLA> S;
;         const int total = 512; int L = F.vcu, pass = 0;
;         if (L < total) {
;             att::BlockRef cur = mla_ref(ws, L, 0);
;             att::prime<CfgMLA>(cur, lds, S);
.LBB0_456:
	s_cmp_lt_i32 s2, 6
	s_cselect_b64 s[0:1], -1, 0
	s_cmp_gt_i32 s3, 5
	s_cselect_b64 s[2:3], -1, 0
	s_and_b64 s[0:1], s[0:1], s[2:3]
	v_writelane_b32 v240, s0, 12
	s_andn2_b64 vcc, exec, s[0:1]
	s_nop 0
	v_writelane_b32 v240, s1, 13
	s_cbranch_vccnz .LBB0_771
	v_readlane_b32 s0, v240, 2
	s_cmpk_gt_i32 s0, 0x1ff
	s_cbranch_scc1 .LBB0_771
	v_readfirstlane_b32 s0, v222
	s_lshr_b32 s0, s0, 6
	s_cmp_ge_u32 s0, 4
	s_cbranch_scc1 .Lprio5_skip
	s_setprio 1
